# v36 + StaticOrder::next in all 10 GEMM tile loops: the signed division by the tile-group height (always 8 for these shapes) replaced by a shift (drops the float-reciprocal / readfirstlane / correction
# baseline (speedup 1.0000x reference)
;     __device__ __forceinline__ bool next(int i, Unit& u) const {
;         const long L = (long)i * G + c; if (L >= nwg) return false;
;         int wgid = (int)L; { const int q = nwg / NXCD, r = nwg % NXCD, xcd = wgid % NXCD, off = wgid / NXCD; wgid = (xcd < r ? xcd * (q + 1) : r * (q + 1) + (xcd - r) * q) + off; }
;         const int nig = WGM * nN, gid = wgid / nig, fm = gid * WGM, gsz = (nM - fm) < WGM ? (nM - fm) : WGM;
;         u.pm = fm + ((wgid % nig) % gsz); u.pn = (wgid % nig) / gsz; return true;
.LBB0_162:
	s_add_i32 s43, s43, 1
	v_readlane_b32 s0, v252, 18
	v_readlane_b32 s6, v251, 4
	s_mul_i32 s0, s43, s0
	v_readlane_b32 s7, v251, 5
	s_mul_hi_u32 s1, s43, s6
	s_add_i32 s1, s1, s0
	s_mul_i32 s0, s43, s6
	v_readlane_b32 s6, v252, 36
	v_readlane_b32 s7, v252, 37
	s_add_u32 s20, s0, s6
	s_addc_u32 s21, s1, s7
	v_mov_b64_e32 v[2:3], 0x1600
	v_cmp_lt_i64_e64 s[0:1], s[20:21], v[2:3]
	v_mov_b64_e32 v[2:3], 0x15ff
	v_cmp_gt_i64_e32 vcc, s[20:21], v[2:3]
	s_cbranch_vccnz .LBB0_164
	s_ashr_i32 s6, s20, 31
	s_lshr_b32 s6, s6, 29
	s_add_i32 s6, s20, s6
	s_ashr_i32 s7, s6, 3
	s_and_b32 s6, s6, -8
	s_sub_i32 s6, s20, s6
	s_cmp_lt_i32 s6, 0
	s_movk_i32 s10, 0x2c1
	s_cselect_b32 s10, s10, 0x2c0
	s_mul_i32 s6, s6, s10
	s_add_i32 s6, s6, s7
	s_mul_hi_i32 s7, s6, 0x2e8ba2e9
	s_lshr_b32 s10, s7, 31
	s_ashr_i32 s7, s7, 5
	s_add_i32 s7, s7, s10
	s_lshl_b32 s10, s7, 3
	s_sub_i32 s11, 0x100, s10
	s_min_i32 s11, s11, 8
	s_mulk_i32 s7, 0xb0
	s_sub_i32 s6, s6, s7
	s_lshr_b32 s16, s6, 3
	s_mul_i32 s7, s16, s11
	s_sub_i32 s6, s6, s7
	s_add_i32 s18, s10, s6

;     __device__ __forceinline__ bool next(int i, Unit& u) const {
;     ...
;         int wgid = (int)L; { const int q = nwg / NXCD, r = nwg % NXCD, xcd = wgid % NXCD, off = wgid / NXCD; wgid = (xcd < r ? xcd * (q + 1) : r * (q + 1) + (xcd - r) * q) + off; }
;         const int nig = WGM * nN, gid = wgid / nig, fm = gid * WGM, gsz = (nM - fm) < WGM ? (nM - fm) : WGM;
;         u.pm = fm + ((wgid % nig) % gsz); u.pn = (wgid % nig) / gsz; return true;
.LBB0_235:
	s_ashr_i32 s6, s6, 3
	s_add_i32 s6, s10, s6
	s_ashr_i32 s7, s6, 31
	s_lshr_b32 s7, s7, 27
	s_add_i32 s7, s6, s7
	s_ashr_i32 s10, s7, 5
	s_lshl_b32 s10, s10, 3
	s_sub_i32 s11, 0x100, s10
	s_min_i32 s11, s11, 8
	s_andn2_b32 s7, s7, 31
	s_sub_i32 s6, s6, s7
	s_lshr_b32 s29, s6, 3
	s_mul_i32 s7, s29, s11
	s_sub_i32 s6, s6, s7
	s_add_i32 s30, s10, s6

;     __device__ __forceinline__ bool next(int i, Unit& u) const {
;     ...
;         int wgid = (int)L; { const int q = nwg / NXCD, r = nwg % NXCD, xcd = wgid % NXCD, off = wgid / NXCD; wgid = (xcd < r ? xcd * (q + 1) : r * (q + 1) + (xcd - r) * q) + off; }
;         const int nig = WGM * nN, gid = wgid / nig, fm = gid * WGM, gsz = (nM - fm) < WGM ? (nM - fm) : WGM;
;         u.pm = fm + ((wgid % nig) % gsz); u.pn = (wgid % nig) / gsz; return true;
.LBB0_325:
	s_add_i32 s18, s18, 1
	v_readlane_b32 s6, v252, 18
	s_mul_i32 s6, s18, s6
	s_mul_hi_u32 s7, s18, s30
	s_add_i32 s7, s7, s6
	s_mul_i32 s6, s18, s30
	v_readlane_b32 s10, v252, 36
	v_readlane_b32 s11, v252, 37
	s_add_u32 s24, s6, s10
	s_addc_u32 s25, s7, s11
	v_mov_b64_e32 v[2:3], 0x1080
	v_cmp_lt_i64_e64 s[48:49], s[24:25], v[2:3]
	v_mov_b64_e32 v[2:3], 0x107f
	v_cmp_gt_i64_e32 vcc, s[24:25], v[2:3]
	s_cbranch_vccnz .LBB0_327
	s_ashr_i32 s6, s24, 31
	s_lshr_b32 s6, s6, 29
	s_add_i32 s6, s24, s6
	s_ashr_i32 s7, s6, 3
	s_and_b32 s6, s6, -8
	s_sub_i32 s6, s24, s6
	s_cmp_lt_i32 s6, 0
	s_cselect_b32 s10, s94, 0x210
	s_mul_i32 s6, s6, s10
	s_add_i32 s6, s6, s7
	s_mul_hi_i32 s7, s6, 0x3e0f83e1
	s_lshr_b32 s10, s7, 31
	s_ashr_i32 s7, s7, 6
	s_add_i32 s7, s7, s10
	s_lshl_b32 s10, s7, 3
	s_sub_i32 s11, 0x80, s10
	s_min_i32 s11, s11, 8
	s_mulk_i32 s7, 0x108
	s_sub_i32 s6, s6, s7
	s_lshr_b32 s20, s6, 3
	s_mul_i32 s7, s20, s11
	s_sub_i32 s6, s6, s7
	s_add_i32 s22, s10, s6

;     __device__ __forceinline__ bool next(int i, Unit& u) const {
;     ...
;         int wgid = (int)L; { const int q = nwg / NXCD, r = nwg % NXCD, xcd = wgid % NXCD, off = wgid / NXCD; wgid = (xcd < r ? xcd * (q + 1) : r * (q + 1) + (xcd - r) * q) + off; }
;         const int nig = WGM * nN, gid = wgid / nig, fm = gid * WGM, gsz = (nM - fm) < WGM ? (nM - fm) : WGM;
;         u.pm = fm + ((wgid % nig) % gsz); u.pn = (wgid % nig) / gsz; return true;
.LBB0_558:
	s_add_i32 s37, s37, 1
	v_readlane_b32 s0, v252, 18
	v_readlane_b32 s6, v251, 4
	s_mul_i32 s0, s37, s0
	v_readlane_b32 s7, v251, 5
	s_mul_hi_u32 s1, s37, s6
	s_add_i32 s1, s1, s0
	s_mul_i32 s0, s37, s6
	v_readlane_b32 s6, v252, 36
	v_readlane_b32 s7, v252, 37
	s_add_u32 s16, s0, s6
	s_addc_u32 s17, s1, s7
	v_mov_b64_e32 v[2:3], 0x300
	v_cmp_lt_i64_e64 s[0:1], s[16:17], v[2:3]
	v_mov_b64_e32 v[2:3], 0x2ff
	v_cmp_gt_i64_e32 vcc, s[16:17], v[2:3]
	s_cbranch_vccnz .LBB0_560
	s_ashr_i32 s6, s16, 31
	s_lshr_b32 s6, s6, 29
	s_add_i32 s6, s16, s6
	s_ashr_i32 s7, s6, 3
	s_and_b32 s6, s6, -8
	s_sub_i32 s6, s16, s6
	s_cmp_lt_i32 s6, 0
	s_movk_i32 s10, 0x61
	s_cselect_b32 s10, s10, 0x60
	s_mul_i32 s6, s6, s10
	s_add_i32 s6, s6, s7
	s_mul_hi_i32 s7, s6, 0x2aaaaaab
	s_lshr_b32 s10, s7, 31
	s_ashr_i32 s7, s7, 3
	s_add_i32 s7, s7, s10
	s_lshl_b32 s10, s7, 3
	s_sub_i32 s11, 0x80, s10
	s_min_i32 s11, s11, 8
	s_mul_i32 s7, s7, 48
	s_sub_i32 s6, s6, s7
	s_lshr_b32 s38, s6, 3
	s_mul_i32 s7, s38, s11
	s_sub_i32 s6, s6, s7
	s_add_i32 s39, s10, s6

;     __device__ __forceinline__ bool next(int i, Unit& u) const {
;     ...
;         int wgid = (int)L; { const int q = nwg / NXCD, r = nwg % NXCD, xcd = wgid % NXCD, off = wgid / NXCD; wgid = (xcd < r ? xcd * (q + 1) : r * (q + 1) + (xcd - r) * q) + off; }
;         const int nig = WGM * nN, gid = wgid / nig, fm = gid * WGM, gsz = (nM - fm) < WGM ? (nM - fm) : WGM;
;         u.pm = fm + ((wgid % nig) % gsz); u.pn = (wgid % nig) / gsz; return true;
.LBB0_631:
	s_ashr_i32 s6, s6, 3
	s_add_i32 s6, s10, s6
	s_ashr_i32 s7, s6, 31
	s_lshr_b32 s7, s7, 26
	s_add_i32 s7, s6, s7
	s_ashr_i32 s10, s7, 6
	s_lshl_b32 s10, s10, 3
	s_sub_i32 s11, 0x80, s10
	s_min_i32 s11, s11, 8
	s_andn2_b32 s7, s7, 63
	s_sub_i32 s6, s6, s7
	s_lshr_b32 s16, s6, 3
	s_mul_i32 s7, s16, s11
	s_sub_i32 s6, s6, s7
	s_add_i32 s94, s10, s6

;     __device__ __forceinline__ bool next(int i, Unit& u) const {
;     ...
;         int wgid = (int)L; { const int q = nwg / NXCD, r = nwg % NXCD, xcd = wgid % NXCD, off = wgid / NXCD; wgid = (xcd < r ? xcd * (q + 1) : r * (q + 1) + (xcd - r) * q) + off; }
;         const int nig = WGM * nN, gid = wgid / nig, fm = gid * WGM, gsz = (nM - fm) < WGM ? (nM - fm) : WGM;
;         u.pm = fm + ((wgid % nig) % gsz); u.pn = (wgid % nig) / gsz; return true;
.LBB0_1064:
	s_ashr_i32 s6, s6, 3
	s_add_i32 s6, s10, s6
	s_ashr_i32 s7, s6, 31
	s_lshr_b32 s7, s7, 27
	s_add_i32 s7, s6, s7
	s_ashr_i32 s10, s7, 5
	s_lshl_b32 s10, s10, 3
	s_sub_i32 s11, 0x80, s10
	s_min_i32 s11, s11, 8
	s_andn2_b32 s7, s7, 31
	s_sub_i32 s6, s6, s7
	s_lshr_b32 s20, s6, 3
	s_mul_i32 s7, s20, s11
	s_sub_i32 s6, s6, s7
	s_add_i32 s54, s10, s6

;     __device__ __forceinline__ bool next(int i, Unit& u) const {
;         const long L = (long)i * G + c; if (L >= nwg) return false;
;         int wgid = (int)L; { const int q = nwg / NXCD, r = nwg % NXCD, xcd = wgid % NXCD, off = wgid / NXCD; wgid = (xcd < r ? xcd * (q + 1) : r * (q + 1) + (xcd - r) * q) + off; }
;         const int nig = WGM * nN, gid = wgid / nig, fm = gid * WGM, gsz = (nM - fm) < WGM ? (nM - fm) : WGM;
;         u.pm = fm + ((wgid % nig) % gsz); u.pn = (wgid % nig) / gsz; return true;
.LBB0_1148:
	s_add_i32 s38, s38, 1
	v_readlane_b32 s6, v252, 18
	v_readlane_b32 s10, v251, 4
	s_mul_i32 s6, s38, s6
	v_readlane_b32 s11, v251, 5
	s_mul_hi_u32 s7, s38, s10
	s_add_i32 s7, s7, s6
	s_mul_i32 s6, s38, s10
	v_readlane_b32 s10, v252, 36
	v_readlane_b32 s11, v252, 37
	s_add_u32 s18, s6, s10
	s_addc_u32 s19, s7, s11
	v_mov_b64_e32 v[2:3], 0x1600
	v_cmp_lt_i64_e64 s[42:43], s[18:19], v[2:3]
	v_mov_b64_e32 v[2:3], 0x15ff
	v_cmp_gt_i64_e32 vcc, s[18:19], v[2:3]
	s_cbranch_vccnz .LBB0_1150
	s_ashr_i32 s6, s18, 31
	s_lshr_b32 s6, s6, 29
	s_add_i32 s6, s18, s6
	s_ashr_i32 s7, s6, 3
	s_and_b32 s6, s6, -8
	s_sub_i32 s6, s18, s6
	s_cmp_lt_i32 s6, 0
	s_movk_i32 s10, 0x2c1
	s_cselect_b32 s10, s10, 0x2c0
	s_mul_i32 s6, s6, s10
	s_add_i32 s6, s6, s7
	s_mul_hi_i32 s7, s6, 0x2e8ba2e9
	s_lshr_b32 s10, s7, 31
	s_ashr_i32 s7, s7, 5
	s_add_i32 s7, s7, s10
	s_lshl_b32 s10, s7, 3
	s_sub_i32 s11, 0x100, s10
	s_min_i32 s11, s11, 8
	s_mulk_i32 s7, 0xb0
	s_sub_i32 s6, s6, s7
	s_lshr_b32 s14, s6, 3
	s_mul_i32 s7, s14, s11
	s_sub_i32 s6, s6, s7
	s_add_i32 s16, s10, s6

;     __device__ __forceinline__ bool next(int i, Unit& u) const {
;     ...
;         int wgid = (int)L; { const int q = nwg / NXCD, r = nwg % NXCD, xcd = wgid % NXCD, off = wgid / NXCD; wgid = (xcd < r ? xcd * (q + 1) : r * (q + 1) + (xcd - r) * q) + off; }
;         const int nig = WGM * nN, gid = wgid / nig, fm = gid * WGM, gsz = (nM - fm) < WGM ? (nM - fm) : WGM;
;         u.pm = fm + ((wgid % nig) % gsz); u.pn = (wgid % nig) / gsz; return true;
.LBB0_1169:
	s_ashr_i32 s0, s0, 3
	s_add_i32 s0, s6, s0
	s_ashr_i32 s1, s0, 31
	s_lshr_b32 s1, s1, 27
	s_add_i32 s1, s0, s1
	s_ashr_i32 s6, s1, 5
	s_lshl_b32 s6, s6, 3
	s_sub_i32 s7, 0x100, s6
	s_min_i32 s7, s7, 8
	s_andn2_b32 s1, s1, 31
	s_sub_i32 s0, s0, s1
	s_lshr_b32 s14, s0, 3
	s_mul_i32 s1, s14, s7
	s_sub_i32 s0, s0, s1
	s_add_i32 s16, s6, s0

;     __device__ __forceinline__ bool next(int i, Unit& u) const {
;     ...
;         int wgid = (int)L; { const int q = nwg / NXCD, r = nwg % NXCD, xcd = wgid % NXCD, off = wgid / NXCD; wgid = (xcd < r ? xcd * (q + 1) : r * (q + 1) + (xcd - r) * q) + off; }
;         const int nig = WGM * nN, gid = wgid / nig, fm = gid * WGM, gsz = (nM - fm) < WGM ? (nM - fm) : WGM;
;         u.pm = fm + ((wgid % nig) % gsz); u.pn = (wgid % nig) / gsz; return true;
.LBB0_1333:
	s_ashr_i32 s6, s6, 3
	s_add_i32 s6, s10, s6
	s_ashr_i32 s7, s6, 31
	s_lshr_b32 s7, s7, 27
	s_add_i32 s7, s6, s7
	s_ashr_i32 s10, s7, 5
	s_lshl_b32 s10, s10, 3
	s_sub_i32 s11, 0x100, s10
	s_min_i32 s11, s11, 8
	s_andn2_b32 s7, s7, 31
	s_sub_i32 s6, s6, s7
	s_lshr_b32 s56, s6, 3
	s_mul_i32 s7, s56, s11
	s_sub_i32 s6, s6, s7
	s_add_i32 s48, s10, s6
